# row norms: 64-lane sums by DPP + row_bcast instead of six ds_bpermute round trips (row_pre, ROW_P1, ROW_HG)
# speedup vs baseline: 1.0098x; 1.0055x over previous
; __device__ __forceinline__ float row_rstd(const f32x4 (&v)[8]) {
;     float s = 0.f;
; #pragma unroll
;     for (int j = 0; j < 8; ++j) s += (v[j][0] * v[j][0] + v[j][1] * v[j][1]) + (v[j][2] * v[j][2] + v[j][3] * v[j][3]);
;     return rsqrtf(wave_sum(s) * (1.f / D) + 1e-6f);
; __device__ __forceinline__ void row_pre(const Params& p, int layer) {
;     ...
;                 f32x4 dn[8]; row_load_bf16(DOWN + (size_t)m * D, lane, dn);
;                 const float rs = row_rstd(dn);
; #pragma unroll
;                 for (int j = 0; j < 8; ++j) { const f32x4 g = *(const f32x4*)(gpost + 256 * j + 4 * lane); x[j] += dn[j] * rs * g; }
.LBB0_641:
	s_andn2_b64 vcc, exec, s[40:41]
	s_cbranch_vccnz .LBB0_662
	s_cmp_lt_i32 s37, 0
	s_waitcnt vmcnt(7)
	v_and_b32_e32 v141, 0xffff0000, v231
	v_and_b32_e32 v139, 0xffff0000, v230
	v_lshlrev_b32_e32 v140, 16, v231
	v_mul_f32_e32 v2, v141, v141
	s_waitcnt vmcnt(4)
	v_lshlrev_b32_e32 v121, 16, v232
	v_and_b32_e32 v119, 0xffff0000, v232
	v_lshlrev_b32_e32 v116, 16, v233
	v_and_b32_e32 v117, 0xffff0000, v233
	s_waitcnt vmcnt(0)
	v_lshlrev_b32_e32 v111, 16, v228
	v_and_b32_e32 v109, 0xffff0000, v228
	v_lshlrev_b32_e32 v106, 16, v229
	v_and_b32_e32 v107, 0xffff0000, v229
	v_lshlrev_b32_e32 v138, 16, v230
	v_pk_fma_f32 v[68:69], v[140:141], v[140:141], v[2:3] op_sel_hi:[1,1,0]
	v_and_b32_e32 v137, 0xffff0000, v113
	v_and_b32_e32 v136, 0xffff0000, v112
	v_mul_f32_e32 v2, v139, v139
	v_lshlrev_b32_e32 v131, 16, v113
	v_lshlrev_b32_e32 v130, 16, v112
	v_pk_mul_f32 v[70:71], v[136:137], v[136:137]
	v_pk_fma_f32 v[112:113], v[138:139], v[138:139], v[2:3] op_sel_hi:[1,1,0]
	v_pk_fma_f32 v[70:71], v[130:131], v[130:131], v[70:71]
	v_lshlrev_b32_e32 v126, 16, v114
	v_and_b32_e32 v127, 0xffff0000, v114
	v_lshlrev_b32_e32 v128, 16, v115
	v_and_b32_e32 v129, 0xffff0000, v115
	v_mov_b32_e32 v120, v112
	v_mov_b32_e32 v114, v68
	v_mov_b32_e32 v115, v121
	v_mul_f32_e32 v1, v119, v119
	v_pk_add_f32 v[68:69], v[112:113], v[68:69]
	v_pk_mul_f32 v[112:113], v[120:121], v[114:115]
	v_pk_add_f32 v[70:71], v[70:71], v[70:71] op_sel:[0,1] op_sel_hi:[1,0]
	v_mov_b32_e32 v69, v113
	v_mov_b32_e32 v71, v1
	v_mul_f32_e32 v2, v127, v127
	v_pk_add_f32 v[68:69], v[68:69], v[70:71]
	v_pk_fma_f32 v[70:71], v[126:127], v[126:127], v[2:3] op_sel_hi:[1,1,0]
	v_mul_f32_e32 v2, v129, v129
	v_mul_f32_e32 v73, v116, v116
	v_mul_f32_e32 v108, v117, v117
	v_pk_fma_f32 v[112:113], v[128:129], v[128:129], v[2:3] op_sel_hi:[1,1,0]
	v_mov_b32_e32 v71, v73
	v_mov_b32_e32 v113, v108
	v_pk_add_f32 v[70:71], v[70:71], v[112:113]
	v_lshlrev_b32_e32 v123, 16, v125
	v_lshlrev_b32_e32 v122, 16, v124
	v_and_b32_e32 v125, 0xffff0000, v125
	v_and_b32_e32 v124, 0xffff0000, v124
	v_pk_add_f32 v[158:159], v[68:69], v[70:71]
	v_pk_mul_f32 v[68:69], v[124:125], v[124:125]
	v_and_b32_e32 v115, 0xffff0000, v143
	v_pk_fma_f32 v[68:69], v[122:123], v[122:123], v[68:69]
	v_and_b32_e32 v114, 0xffff0000, v142
	v_pk_add_f32 v[160:161], v[68:69], v[68:69] op_sel:[0,1] op_sel_hi:[1,0]
	v_lshlrev_b32_e32 v113, 16, v143
	v_lshlrev_b32_e32 v112, 16, v142
	v_pk_mul_f32 v[68:69], v[114:115], v[114:115]
	v_lshlrev_b32_e32 v70, 16, v145
	v_pk_fma_f32 v[142:143], v[112:113], v[112:113], v[68:69]
	v_lshlrev_b32_e32 v68, 16, v144
	v_and_b32_e32 v69, 0xffff0000, v144
	v_and_b32_e32 v71, 0xffff0000, v145
	v_pk_add_f32 v[144:145], v[158:159], v[158:159] op_sel:[0,1] op_sel_hi:[1,0]
	v_mov_b32_e32 v158, v160
	v_mov_b32_e32 v110, v144
	v_mov_b32_e32 v159, v111
	v_mul_f32_e32 v1, v109, v109
	v_pk_add_f32 v[144:145], v[144:145], v[160:161]
	v_pk_mul_f32 v[158:159], v[110:111], v[158:159]
	v_pk_add_f32 v[142:143], v[142:143], v[142:143] op_sel:[0,1] op_sel_hi:[1,0]
	v_mov_b32_e32 v145, v159
	v_mov_b32_e32 v143, v1
	v_mul_f32_e32 v2, v69, v69
	v_pk_add_f32 v[142:143], v[144:145], v[142:143]
	v_pk_fma_f32 v[144:145], v[68:69], v[68:69], v[2:3] op_sel_hi:[1,1,0]
	v_mul_f32_e32 v2, v71, v71
	v_mul_f32_e32 v73, v106, v106
	v_mul_f32_e32 v108, v107, v107
	v_pk_fma_f32 v[158:159], v[70:71], v[70:71], v[2:3] op_sel_hi:[1,1,0]
	v_mov_b32_e32 v145, v73
	v_mov_b32_e32 v159, v108
	v_pk_add_f32 v[144:145], v[144:145], v[158:159]
	v_pk_add_f32 v[142:143], v[142:143], v[144:145]
	v_add_f32_e32 v1, v142, v143
	v_mov_b32_e32 v118, v121
	v_mov_b32_e32 v120, v122
	v_mov_b32_e32 v121, v124
	v_mov_b32_e32 v124, v123
	v_mov_b32_e32 v108, v111
	s_waitcnt lgkmcnt(0)
	s_nop 1
	v_add_f32_dpp v1, v1, v1 quad_perm:[1,0,3,2] row_mask:0xf bank_mask:0xf bound_ctrl:1
	s_nop 1
	v_add_f32_dpp v1, v1, v1 quad_perm:[2,3,0,1] row_mask:0xf bank_mask:0xf bound_ctrl:1
	s_nop 1
	v_add_f32_dpp v1, v1, v1 row_half_mirror row_mask:0xf bank_mask:0xf bound_ctrl:1
	s_nop 1
	v_add_f32_dpp v1, v1, v1 row_mirror row_mask:0xf bank_mask:0xf bound_ctrl:1
	s_nop 1
	v_add_f32_dpp v1, v1, v1 row_bcast:15 row_mask:0xa bank_mask:0xf
	s_nop 1
	v_add_f32_dpp v1, v1, v1 row_bcast:31 row_mask:0xc bank_mask:0xf
	s_nop 1
	v_readlane_b32 vcc_lo, v1, 63
	s_nop 2
	v_mov_b32_e32 v1, vcc_lo
	v_fmamk_f32 v1, v1, 0x3a000000, v147
	v_cmp_gt_f32_e32 vcc, s29, v1
	v_mul_f32_e32 v2, 0x4b800000, v1
	s_nop 0
	v_cndmask_b32_e32 v1, v1, v2, vcc
	v_rsq_f32_e32 v1, v1
	s_nop 0
	v_mul_f32_e32 v2, 0x45800000, v1
	v_cndmask_b32_e32 v2, v1, v2, vcc
	v_pk_mul_f32 v[138:139], v[2:3], v[138:139] op_sel_hi:[0,1]
	v_pk_mul_f32 v[140:141], v[2:3], v[140:141] op_sel_hi:[0,1]
	v_pk_fma_f32 v[66:67], v[198:199], v[140:141], v[66:67]
	v_pk_fma_f32 v[64:65], v[196:197], v[138:139], v[64:65]
	v_mov_b32_e32 v142, v130
	v_mov_b32_e32 v143, v136
	v_pk_mul_f32 v[142:143], v[2:3], v[142:143] op_sel_hi:[0,1]
	v_mov_b32_e32 v136, v131
	v_pk_mul_f32 v[130:131], v[2:3], v[136:137] op_sel_hi:[0,1]
	v_pk_mul_f32 v[126:127], v[2:3], v[126:127] op_sel_hi:[0,1]
	v_pk_mul_f32 v[128:129], v[2:3], v[128:129] op_sel_hi:[0,1]
	v_pk_mul_f32 v[118:119], v[2:3], v[118:119] op_sel_hi:[0,1]
	v_pk_mul_f32 v[116:117], v[2:3], v[116:117] op_sel_hi:[0,1]
	v_pk_mul_f32 v[120:121], v[2:3], v[120:121] op_sel_hi:[0,1]
	v_pk_mul_f32 v[122:123], v[2:3], v[124:125] op_sel_hi:[0,1]
	v_pk_mul_f32 v[68:69], v[2:3], v[68:69] op_sel_hi:[0,1]
	v_pk_mul_f32 v[70:71], v[2:3], v[70:71] op_sel_hi:[0,1]
	v_pk_mul_f32 v[108:109], v[2:3], v[108:109] op_sel_hi:[0,1]
	v_pk_mul_f32 v[106:107], v[2:3], v[106:107] op_sel_hi:[0,1]
	v_pk_fma_f32 v[60:61], v[200:201], v[142:143], v[60:61]
	v_pk_fma_f32 v[62:63], v[202:203], v[130:131], v[62:63]
	v_pk_fma_f32 v[58:59], v[206:207], v[128:129], v[58:59]
	v_pk_fma_f32 v[56:57], v[204:205], v[126:127], v[56:57]
	v_pk_fma_f32 v[50:51], v[210:211], v[116:117], v[50:51]
	v_pk_fma_f32 v[48:49], v[208:209], v[118:119], v[48:49]
	v_pk_fma_f32 v[54:55], v[214:215], v[122:123], v[54:55]
	v_pk_fma_f32 v[52:53], v[212:213], v[120:121], v[52:53]
	v_mov_b32_e32 v121, v114
	v_mov_b32_e32 v114, v113
	v_mov_b32_e32 v120, v112
	v_pk_mul_f32 v[112:113], v[2:3], v[114:115] op_sel_hi:[0,1]
	v_pk_mul_f32 v[120:121], v[2:3], v[120:121] op_sel_hi:[0,1]
	v_pk_fma_f32 v[46:47], v[218:219], v[112:113], v[46:47]
	v_pk_fma_f32 v[44:45], v[216:217], v[120:121], v[44:45]
	v_pk_fma_f32 v[42:43], v[222:223], v[70:71], v[42:43]
	v_pk_fma_f32 v[40:41], v[220:221], v[68:69], v[40:41]
	v_pk_fma_f32 v[38:39], v[226:227], v[106:107], v[38:39]
	v_pk_fma_f32 v[36:37], v[224:225], v[108:109], v[36:37]
	s_cbranch_scc1 .LBB0_662
	s_lshl_b64 s[18:19], s[16:17], 11
	v_lshl_add_u64 v[68:69], s[18:19], 1, v[80:81]
	s_mov_b64 s[4:5], -1
	s_and_b64 vcc, exec, s[6:7]
	s_cbranch_vccz .LBB0_645
	v_cvt_pk_bf16_f32 v70, v64, v65
	v_cvt_pk_bf16_f32 v71, v66, v67
	global_store_dwordx2 v[68:69], v[70:71], off
	s_mov_b64 s[4:5], 0

; __device__ __forceinline__ unsigned pk2(float lo, float hi) { f32x2c v = {lo, hi}; return __builtin_bit_cast(unsigned, __builtin_convertvector(v, bf16x2c)); }
; __device__ __forceinline__ float row_rstd(const f32x4 (&v)[8]) {
;     float s = 0.f;
; #pragma unroll
;     for (int j = 0; j < 8; ++j) s += (v[j][0] * v[j][0] + v[j][1] * v[j][1]) + (v[j][2] * v[j][2] + v[j][3] * v[j][3]);
;     return rsqrtf(wave_sum(s) * (1.f / D) + 1e-6f);
; }
; __device__ __forceinline__ void row_store_bf16(bf16_t* p, int lane, const f32x4 (&v)[8]) {
; #pragma unroll
;     for (int j = 0; j < 8; ++j) { u32x2 w; w.x = pk2(v[j][0], v[j][1]); w.y = pk2(v[j][2], v[j][3]); *(u32x2*)(p + 256 * j + 4 * lane) = w; }
; }
; __device__ __forceinline__ void row_pre(const Params& p, int layer) {
;     ...
;             if (layer == 4) continue;
;             const float rs = row_rstd(x);
; #pragma unroll
;             for (int j = 0; j < 8; ++j) { const f32x4 g = *(const f32x4*)(gpre + 256 * j + 4 * lane); x[j] = x[j] * rs * g; }
;             if (!odd) { row_store_bf16((bf16_t*)(ws + WS_HB) + (size_t)m * D, lane, x); continue; }
.LBB0_662:
	s_andn2_b64 vcc, exec, s[6:7]
	s_cbranch_vccnz .LBB0_673
	s_waitcnt vmcnt(7)
	v_pk_mul_f32 v[114:115], v[64:65], v[64:65]
	s_waitcnt vmcnt(6)
	v_pk_mul_f32 v[116:117], v[60:61], v[60:61]
	v_pk_mul_f32 v[110:111], v[66:67], v[66:67]
	v_pk_mul_f32 v[112:113], v[62:63], v[62:63]
	v_mov_b32_e32 v118, v114
	v_mov_b32_e32 v119, v116
	v_mov_b32_e32 v116, v115
	s_waitcnt vmcnt(5)
	v_pk_mul_f32 v[106:107], v[58:59], v[58:59]
	v_pk_mul_f32 v[108:109], v[56:57], v[56:57]
	v_pk_add_f32 v[114:115], v[118:119], v[116:117]
	v_mov_b32_e32 v116, v110
	v_mov_b32_e32 v117, v112
	v_mov_b32_e32 v112, v111
	v_pk_add_f32 v[110:111], v[116:117], v[112:113]
	v_pk_mov_b32 v[112:113], v[108:109], v[106:107] op_sel:[1,0]
	v_mov_b32_e32 v109, v107
	s_waitcnt vmcnt(4)
	v_mul_f32_e32 v2, v48, v48
	v_pk_add_f32 v[110:111], v[114:115], v[110:111]
	v_pk_add_f32 v[106:107], v[112:113], v[108:109]
	v_pk_fma_f32 v[108:109], v[48:49], v[48:49], v[2:3] op_sel_hi:[1,1,0]
	v_mul_f32_e32 v2, v50, v50
	v_pk_add_f32 v[110:111], v[110:111], v[110:111] op_sel_hi:[0,1]
	v_pk_add_f32 v[106:107], v[106:107], v[106:107] op_sel_hi:[0,1]
	v_pk_fma_f32 v[112:113], v[50:51], v[50:51], v[2:3] op_sel_hi:[1,1,0]
	s_waitcnt vmcnt(3)
	v_mul_f32_e32 v108, v52, v52
	v_mul_f32_e32 v112, v53, v53
	v_mul_f32_e32 v106, v54, v54
	v_mul_f32_e32 v110, v55, v55
	s_waitcnt vmcnt(2)
	v_pk_mul_f32 v[68:69], v[46:47], v[46:47]
	v_pk_mul_f32 v[70:71], v[44:45], v[44:45]
	v_pk_add_f32 v[108:109], v[108:109], v[112:113]
	v_pk_add_f32 v[106:107], v[106:107], v[110:111]
	s_waitcnt vmcnt(1)
	v_mul_f32_e32 v2, v40, v40
	v_pk_add_f32 v[106:107], v[108:109], v[106:107]
	v_pk_mov_b32 v[108:109], v[70:71], v[68:69] op_sel:[1,0]
	v_mov_b32_e32 v71, v69
	v_pk_add_f32 v[68:69], v[108:109], v[70:71]
	v_pk_fma_f32 v[70:71], v[40:41], v[40:41], v[2:3] op_sel_hi:[1,1,0]
	v_mul_f32_e32 v2, v42, v42
	v_pk_add_f32 v[106:107], v[106:107], v[106:107] op_sel_hi:[0,1]
	v_pk_add_f32 v[68:69], v[68:69], v[68:69] op_sel_hi:[0,1]
	v_pk_fma_f32 v[108:109], v[42:43], v[42:43], v[2:3] op_sel_hi:[1,1,0]
	s_waitcnt vmcnt(0)
	v_mul_f32_e32 v70, v36, v36
	v_mul_f32_e32 v108, v37, v37
	v_mul_f32_e32 v68, v38, v38
	v_mul_f32_e32 v106, v39, v39
	v_pk_add_f32 v[70:71], v[70:71], v[108:109]
	v_pk_add_f32 v[68:69], v[68:69], v[106:107]
	global_load_dwordx4 v[106:109], v[82:83], off offset:1024
	v_pk_add_f32 v[68:69], v[70:71], v[68:69]
	global_load_dwordx4 v[110:113], v[82:83], off offset:2048
	global_load_dwordx4 v[114:117], v[82:83], off offset:3072
	v_add_f32_e32 v1, v68, v69
	global_load_dwordx4 v[68:71], v[82:83], off
	global_load_dwordx4 v[118:121], v[94:95], off
	global_load_dwordx4 v[122:125], v[96:97], off
	global_load_dwordx4 v[126:129], v[98:99], off
	global_load_dwordx4 v[136:139], v[100:101], off
	s_mov_b64 s[4:5], -1
	s_waitcnt lgkmcnt(0)
	s_nop 1
	v_add_f32_dpp v1, v1, v1 quad_perm:[1,0,3,2] row_mask:0xf bank_mask:0xf bound_ctrl:1
	s_nop 1
	v_add_f32_dpp v1, v1, v1 quad_perm:[2,3,0,1] row_mask:0xf bank_mask:0xf bound_ctrl:1
	s_nop 1
	v_add_f32_dpp v1, v1, v1 row_half_mirror row_mask:0xf bank_mask:0xf bound_ctrl:1
	s_nop 1
	v_add_f32_dpp v1, v1, v1 row_mirror row_mask:0xf bank_mask:0xf bound_ctrl:1
	s_nop 1
	v_add_f32_dpp v1, v1, v1 row_bcast:15 row_mask:0xa bank_mask:0xf
	s_nop 1
	v_add_f32_dpp v1, v1, v1 row_bcast:31 row_mask:0xc bank_mask:0xf
	s_nop 1
	v_readlane_b32 vcc_lo, v1, 63
	s_nop 2
	v_mov_b32_e32 v1, vcc_lo
	v_fmamk_f32 v1, v1, 0x3a000000, v147
	v_mul_f32_e32 v2, 0x4b800000, v1
	v_cmp_gt_f32_e32 vcc, s29, v1
	s_nop 1
	v_cndmask_b32_e32 v1, v1, v2, vcc
	v_rsq_f32_e32 v1, v1
	s_nop 0
	v_mul_f32_e32 v2, 0x45800000, v1
	v_cndmask_b32_e32 v2, v1, v2, vcc
	v_pk_mul_f32 v[64:65], v[64:65], v[2:3] op_sel_hi:[1,0]
	v_pk_mul_f32 v[66:67], v[66:67], v[2:3] op_sel_hi:[1,0]
	v_pk_mul_f32 v[60:61], v[60:61], v[2:3] op_sel_hi:[1,0]
	v_pk_mul_f32 v[62:63], v[62:63], v[2:3] op_sel_hi:[1,0]
	v_pk_mul_f32 v[56:57], v[56:57], v[2:3] op_sel_hi:[1,0]
	v_pk_mul_f32 v[58:59], v[58:59], v[2:3] op_sel_hi:[1,0]
	v_pk_mul_f32 v[48:49], v[48:49], v[2:3] op_sel_hi:[1,0]
	v_pk_mul_f32 v[50:51], v[50:51], v[2:3] op_sel_hi:[1,0]
	v_pk_mul_f32 v[52:53], v[52:53], v[2:3] op_sel_hi:[1,0]
	v_pk_mul_f32 v[54:55], v[54:55], v[2:3] op_sel_hi:[1,0]
	v_pk_mul_f32 v[44:45], v[44:45], v[2:3] op_sel_hi:[1,0]
	v_pk_mul_f32 v[46:47], v[46:47], v[2:3] op_sel_hi:[1,0]
	v_pk_mul_f32 v[40:41], v[40:41], v[2:3] op_sel_hi:[1,0]
	v_pk_mul_f32 v[42:43], v[42:43], v[2:3] op_sel_hi:[1,0]
	v_pk_mul_f32 v[36:37], v[36:37], v[2:3] op_sel_hi:[1,0]
	v_pk_mul_f32 v[38:39], v[38:39], v[2:3] op_sel_hi:[1,0]
	s_waitcnt vmcnt(4)
	v_pk_mul_f32 v[66:67], v[70:71], v[66:67]
	v_pk_mul_f32 v[64:65], v[68:69], v[64:65]
	v_pk_mul_f32 v[62:63], v[108:109], v[62:63]
	v_pk_mul_f32 v[60:61], v[106:107], v[60:61]
	v_pk_mul_f32 v[58:59], v[112:113], v[58:59]
	v_pk_mul_f32 v[56:57], v[110:111], v[56:57]
	v_pk_mul_f32 v[50:51], v[116:117], v[50:51]
	v_pk_mul_f32 v[48:49], v[114:115], v[48:49]
	s_waitcnt vmcnt(3)
	v_pk_mul_f32 v[54:55], v[120:121], v[54:55]
	v_pk_mul_f32 v[52:53], v[118:119], v[52:53]
	s_waitcnt vmcnt(2)
	v_pk_mul_f32 v[46:47], v[124:125], v[46:47]
	v_pk_mul_f32 v[44:45], v[122:123], v[44:45]
	s_waitcnt vmcnt(1)
	v_pk_mul_f32 v[42:43], v[128:129], v[42:43]
	v_pk_mul_f32 v[40:41], v[126:127], v[40:41]
	s_waitcnt vmcnt(0)
	v_pk_mul_f32 v[38:39], v[138:139], v[38:39]
	v_pk_mul_f32 v[36:37], v[136:137], v[36:37]
	s_andn2_b64 vcc, exec, s[2:3]
	s_cbranch_vccnz .LBB0_665
	s_ashr_i32 s17, s16, 31
	s_lshl_b64 s[4:5], s[16:17], 12
	v_lshl_add_u64 v[68:69], v[84:85], 0, s[4:5]
	v_cvt_pk_bf16_f32 v70, v64, v65
	v_cvt_pk_bf16_f32 v71, v66, v67
	global_store_dwordx2 v[68:69], v[70:71], off
	v_cvt_pk_bf16_f32 v70, v60, v61
	v_cvt_pk_bf16_f32 v71, v62, v63
	global_store_dwordx2 v[68:69], v[70:71], off offset:512
	v_cvt_pk_bf16_f32 v70, v56, v57
	v_cvt_pk_bf16_f32 v71, v58, v59
	global_store_dwordx2 v[68:69], v[70:71], off offset:1024
	v_cvt_pk_bf16_f32 v70, v48, v49
	v_cvt_pk_bf16_f32 v71, v50, v51
	global_store_dwordx2 v[68:69], v[70:71], off offset:1536
	v_cvt_pk_bf16_f32 v70, v52, v53
	v_cvt_pk_bf16_f32 v71, v54, v55
	global_store_dwordx2 v[68:69], v[70:71], off offset:2048
	v_cvt_pk_bf16_f32 v70, v44, v45
	v_cvt_pk_bf16_f32 v71, v46, v47
	global_store_dwordx2 v[68:69], v[70:71], off offset:2560
	v_cvt_pk_bf16_f32 v70, v40, v41
	v_cvt_pk_bf16_f32 v71, v42, v43
	global_store_dwordx2 v[68:69], v[70:71], off offset:3072
	v_cvt_pk_bf16_f32 v70, v36, v37
	v_cvt_pk_bf16_f32 v71, v38, v39
	s_mov_b64 s[4:5], 0
	global_store_dwordx2 v[68:69], v[70:71], off offset:3584

; __device__ __forceinline__ unsigned pk2(float lo, float hi) { f32x2c v = {lo, hi}; return __builtin_bit_cast(unsigned, __builtin_convertvector(v, bf16x2c)); }
; __device__ __forceinline__ float row_rstd(const f32x4 (&v)[8]) {
;     float s = 0.f;
; #pragma unroll
;     for (int j = 0; j < 8; ++j) s += (v[j][0] * v[j][0] + v[j][1] * v[j][1]) + (v[j][2] * v[j][2] + v[j][3] * v[j][3]);
;     return rsqrtf(wave_sum(s) * (1.f / D) + 1e-6f);
; __device__ __forceinline__ void row_post1(const Params& p, int layer) {
;     ...
;         xrow_load(X, layer == 0, m, lane, x);
;         row_load_bf16(MIX + (size_t)m * D, lane, mx);
;         const float rs = row_rstd(mx);
; #pragma unroll
;         for (int j = 0; j < 8; ++j) { const f32x4 g = *(const f32x4*)(g1 + 256 * j + 4 * lane); x[j] += mx[j] * rs * g; u32x2 w; w.x = pk2(x[j][0], x[j][1]); w.y = pk2(x[j][2], x[j][3]); *(u32x2*)(X + (size_t)m * D + 256 * j + 4 * lane) = w; }
;         const float rs2 = row_rstd(x);
.LBB0_987:
	s_lshl_b64 s[6:7], s[6:7], 12
	v_lshl_add_u64 v[36:37], v[40:41], 0, s[6:7]
	global_load_dwordx2 v[38:39], v[36:37], off
	global_load_dwordx2 v[76:77], v[36:37], off offset:512
	global_load_dwordx2 v[78:79], v[36:37], off offset:1024
	global_load_dwordx2 v[64:65], v[36:37], off offset:1536
	global_load_dwordx2 v[80:81], v[36:37], off offset:2048
	global_load_dwordx2 v[100:101], v[36:37], off offset:2560
	global_load_dwordx2 v[102:103], v[36:37], off offset:3072
	s_nop 0
	global_load_dwordx2 v[36:37], v[36:37], off offset:3584
	s_add_i32 s13, s13, 1
	s_add_i32 s4, s4, s5
	s_cmp_eq_u32 s13, 1
	s_waitcnt vmcnt(7)
	v_and_b32_e32 v97, 0xffff0000, v38
	v_and_b32_e32 v99, 0xffff0000, v39
	v_lshlrev_b32_e32 v96, 16, v38
	v_lshlrev_b32_e32 v98, 16, v39
	s_waitcnt vmcnt(0)
	v_lshlrev_b32_e32 v69, 16, v36
	v_and_b32_e32 v67, 0xffff0000, v36
	v_mul_f32_e32 v36, v99, v99
	v_and_b32_e32 v93, 0xffff0000, v77
	v_and_b32_e32 v92, 0xffff0000, v76
	v_mul_f32_e32 v66, v97, v97
	v_lshlrev_b32_e32 v75, 16, v64
	v_and_b32_e32 v73, 0xffff0000, v64
	v_lshlrev_b32_e32 v70, 16, v65
	v_and_b32_e32 v71, 0xffff0000, v65
	v_lshlrev_b32_e32 v64, 16, v37
	v_and_b32_e32 v65, 0xffff0000, v37
	v_pk_fma_f32 v[36:37], v[98:99], v[98:99], v[36:37] op_sel_hi:[1,1,0]
	v_lshlrev_b32_e32 v95, 16, v77
	v_lshlrev_b32_e32 v94, 16, v76
	v_pk_mul_f32 v[38:39], v[92:93], v[92:93]
	v_pk_fma_f32 v[76:77], v[96:97], v[96:97], v[66:67] op_sel_hi:[1,1,0]
	v_pk_fma_f32 v[38:39], v[94:95], v[94:95], v[38:39]
	v_lshlrev_b32_e32 v88, 16, v78
	v_and_b32_e32 v89, 0xffff0000, v78
	v_lshlrev_b32_e32 v90, 16, v79
	v_and_b32_e32 v91, 0xffff0000, v79
	v_mov_b32_e32 v74, v76
	v_mov_b32_e32 v78, v36
	v_mov_b32_e32 v79, v75
	v_mul_f32_e32 v68, v73, v73
	v_pk_add_f32 v[36:37], v[76:77], v[36:37]
	v_pk_mul_f32 v[76:77], v[74:75], v[78:79]
	v_pk_add_f32 v[38:39], v[38:39], v[38:39] op_sel:[0,1] op_sel_hi:[1,0]
	v_mov_b32_e32 v37, v77
	v_mov_b32_e32 v39, v68
	v_pk_add_f32 v[36:37], v[36:37], v[38:39]
	v_mul_f32_e32 v38, v89, v89
	v_mul_f32_e32 v66, v91, v91
	v_mul_f32_e32 v72, v70, v70
	v_mul_f32_e32 v82, v71, v71
	v_pk_fma_f32 v[38:39], v[88:89], v[88:89], v[38:39] op_sel_hi:[1,1,0]
	v_pk_fma_f32 v[76:77], v[90:91], v[90:91], v[66:67] op_sel_hi:[1,1,0]
	v_mov_b32_e32 v39, v72
	v_mov_b32_e32 v77, v82
	v_pk_add_f32 v[38:39], v[38:39], v[76:77]
	v_and_b32_e32 v85, 0xffff0000, v81
	v_and_b32_e32 v84, 0xffff0000, v80
	v_pk_add_f32 v[36:37], v[36:37], v[38:39]
	v_lshlrev_b32_e32 v87, 16, v81
	v_lshlrev_b32_e32 v86, 16, v80
	v_pk_mul_f32 v[38:39], v[84:85], v[84:85]
	v_and_b32_e32 v81, 0xffff0000, v101
	v_pk_fma_f32 v[38:39], v[86:87], v[86:87], v[38:39]
	v_and_b32_e32 v80, 0xffff0000, v100
	v_pk_add_f32 v[38:39], v[38:39], v[38:39] op_sel:[0,1] op_sel_hi:[1,0]
	v_lshlrev_b32_e32 v83, 16, v101
	v_lshlrev_b32_e32 v82, 16, v100
	v_pk_mul_f32 v[76:77], v[80:81], v[80:81]
	v_pk_add_f32 v[36:37], v[36:37], v[36:37] op_sel:[0,1] op_sel_hi:[1,0]
	v_pk_fma_f32 v[100:101], v[82:83], v[82:83], v[76:77]
	v_lshlrev_b32_e32 v76, 16, v102
	v_and_b32_e32 v77, 0xffff0000, v102
	v_lshlrev_b32_e32 v78, 16, v103
	v_and_b32_e32 v79, 0xffff0000, v103
	v_mov_b32_e32 v68, v36
	v_mov_b32_e32 v102, v38
	v_mov_b32_e32 v103, v69
	v_pk_add_f32 v[36:37], v[36:37], v[38:39]
	v_pk_mul_f32 v[38:39], v[68:69], v[102:103]
	v_mul_f32_e32 v66, v67, v67
	v_mov_b32_e32 v37, v39
	v_pk_add_f32 v[38:39], v[100:101], v[100:101] op_sel:[0,1] op_sel_hi:[1,0]
	v_mul_f32_e32 v72, v64, v64
	v_mov_b32_e32 v39, v66
	v_pk_add_f32 v[36:37], v[36:37], v[38:39]
	v_mul_f32_e32 v38, v77, v77
	v_mul_f32_e32 v66, v79, v79
	v_mul_f32_e32 v74, v65, v65
	v_pk_fma_f32 v[38:39], v[76:77], v[76:77], v[38:39] op_sel_hi:[1,1,0]
	v_pk_fma_f32 v[100:101], v[78:79], v[78:79], v[66:67] op_sel_hi:[1,1,0]
	v_mov_b32_e32 v39, v72
	v_mov_b32_e32 v101, v74
	v_pk_add_f32 v[38:39], v[38:39], v[100:101]
	v_lshl_add_u64 v[100:101], v[0:1], 0, s[6:7]
	v_pk_add_f32 v[36:37], v[36:37], v[38:39]
	v_xor_b32_e32 v38, 1, v152
	v_add_f32_e32 v36, v36, v37
	v_mov_b32_e32 v72, v75
	v_mov_b32_e32 v66, v69
	s_waitcnt lgkmcnt(0)
	s_nop 1
	v_add_f32_dpp v36, v36, v36 quad_perm:[1,0,3,2] row_mask:0xf bank_mask:0xf bound_ctrl:1
	s_nop 1
	v_add_f32_dpp v36, v36, v36 quad_perm:[2,3,0,1] row_mask:0xf bank_mask:0xf bound_ctrl:1
	s_nop 1
	v_add_f32_dpp v36, v36, v36 row_half_mirror row_mask:0xf bank_mask:0xf bound_ctrl:1
	s_nop 1
	v_add_f32_dpp v36, v36, v36 row_mirror row_mask:0xf bank_mask:0xf bound_ctrl:1
	s_nop 1
	v_add_f32_dpp v36, v36, v36 row_bcast:15 row_mask:0xa bank_mask:0xf
	s_nop 1
	v_add_f32_dpp v36, v36, v36 row_bcast:31 row_mask:0xc bank_mask:0xf
	s_nop 1
	v_readlane_b32 vcc_lo, v36, 63
	s_nop 2
	v_mov_b32_e32 v36, vcc_lo
	v_fmamk_f32 v36, v36, 0x3a000000, v147
	v_cmp_gt_f32_e32 vcc, s29, v36
	v_mul_f32_e32 v37, 0x4b800000, v36
	s_nop 0
	v_cndmask_b32_e32 v36, v36, v37, vcc
	v_rsq_f32_e32 v36, v36
	s_nop 0
	v_mul_f32_e32 v37, 0x45800000, v36
	v_cndmask_b32_e32 v68, v36, v37, vcc
	v_pk_mul_f32 v[96:97], v[68:69], v[96:97] op_sel_hi:[0,1]
	v_pk_mul_f32 v[98:99], v[68:69], v[98:99] op_sel_hi:[0,1]
	v_pk_mul_f32 v[88:89], v[68:69], v[88:89] op_sel_hi:[0,1]
	v_pk_mul_f32 v[90:91], v[68:69], v[90:91] op_sel_hi:[0,1]
	v_pk_mul_f32 v[72:73], v[68:69], v[72:73] op_sel_hi:[0,1]
	v_pk_mul_f32 v[70:71], v[68:69], v[70:71] op_sel_hi:[0,1]
	v_pk_mul_f32 v[66:67], v[68:69], v[66:67] op_sel_hi:[0,1]
	v_pk_mul_f32 v[64:65], v[68:69], v[64:65] op_sel_hi:[0,1]
	v_pk_fma_f32 v[34:35], v[162:163], v[98:99], v[34:35]
	v_pk_fma_f32 v[32:33], v[160:161], v[96:97], v[32:33]
	v_cvt_pk_bf16_f32 v37, v34, v35
	v_cvt_pk_bf16_f32 v36, v32, v33
	global_store_dwordx2 v[100:101], v[36:37], off
	v_mov_b32_e32 v96, v94
; __device__ __forceinline__ unsigned pk2(float lo, float hi) { f32x2c v = {lo, hi}; return __builtin_bit_cast(unsigned, __builtin_convertvector(v, bf16x2c)); }
; __device__ __forceinline__ void row_post1(const Params& p, int layer) {
;     ...
;         for (int j = 0; j < 8; ++j) { const f32x4 g = *(const f32x4*)(g1 + 256 * j + 4 * lane); x[j] += mx[j] * rs * g; u32x2 w; w.x = pk2(x[j][0], x[j][1]); w.y = pk2(x[j][2], x[j][3]); *(u32x2*)(X + (size_t)m * D + 256 * j + 4 * lane) = w; }
;         const float rs2 = row_rstd(x);
	v_mov_b32_e32 v97, v92
	v_mov_b32_e32 v92, v95
	v_pk_mul_f32 v[96:97], v[68:69], v[96:97] op_sel_hi:[0,1]
	v_pk_mul_f32 v[92:93], v[68:69], v[92:93] op_sel_hi:[0,1]
	v_pk_fma_f32 v[30:31], v[166:167], v[92:93], v[30:31]
	v_pk_fma_f32 v[28:29], v[164:165], v[96:97], v[28:29]
	v_cvt_pk_bf16_f32 v37, v30, v31
	v_cvt_pk_bf16_f32 v36, v28, v29
	global_store_dwordx2 v[100:101], v[36:37], off offset:512
	v_pk_fma_f32 v[26:27], v[170:171], v[90:91], v[26:27]
	v_pk_fma_f32 v[24:25], v[168:169], v[88:89], v[24:25]
	v_cvt_pk_bf16_f32 v37, v26, v27
	v_cvt_pk_bf16_f32 v36, v24, v25
	global_store_dwordx2 v[100:101], v[36:37], off offset:1024
	v_pk_fma_f32 v[22:23], v[174:175], v[70:71], v[22:23]
	v_pk_fma_f32 v[20:21], v[172:173], v[72:73], v[20:21]
	v_cvt_pk_bf16_f32 v37, v22, v23
	v_cvt_pk_bf16_f32 v36, v20, v21
	global_store_dwordx2 v[100:101], v[36:37], off offset:1536
	v_mov_b32_e32 v70, v86
	v_mov_b32_e32 v71, v84
	v_mov_b32_e32 v84, v87
	v_pk_mul_f32 v[70:71], v[68:69], v[70:71] op_sel_hi:[0,1]
	v_pk_mul_f32 v[72:73], v[68:69], v[84:85] op_sel_hi:[0,1]
	v_pk_fma_f32 v[18:19], v[178:179], v[72:73], v[18:19]
	v_pk_fma_f32 v[16:17], v[176:177], v[70:71], v[16:17]
	v_cvt_pk_bf16_f32 v37, v18, v19
	v_cvt_pk_bf16_f32 v36, v16, v17
	global_store_dwordx2 v[100:101], v[36:37], off offset:2048
	v_mov_b32_e32 v70, v82
	v_mov_b32_e32 v71, v80
	v_mov_b32_e32 v80, v83
	v_pk_mul_f32 v[70:71], v[68:69], v[70:71] op_sel_hi:[0,1]
	v_pk_mul_f32 v[72:73], v[68:69], v[80:81] op_sel_hi:[0,1]
	v_pk_fma_f32 v[14:15], v[182:183], v[72:73], v[14:15]
	v_pk_fma_f32 v[12:13], v[180:181], v[70:71], v[12:13]
	v_cvt_pk_bf16_f32 v37, v14, v15
	v_cvt_pk_bf16_f32 v36, v12, v13
	global_store_dwordx2 v[100:101], v[36:37], off offset:2560
	v_pk_mul_f32 v[70:71], v[68:69], v[76:77] op_sel_hi:[0,1]
	v_pk_mul_f32 v[72:73], v[68:69], v[78:79] op_sel_hi:[0,1]
	v_pk_fma_f32 v[10:11], v[186:187], v[72:73], v[10:11]
	v_pk_fma_f32 v[8:9], v[184:185], v[70:71], v[8:9]
	v_cvt_pk_bf16_f32 v37, v10, v11
	v_cvt_pk_bf16_f32 v36, v8, v9
	global_store_dwordx2 v[100:101], v[36:37], off offset:3072
	v_pk_fma_f32 v[6:7], v[190:191], v[64:65], v[6:7]
	v_pk_fma_f32 v[4:5], v[188:189], v[66:67], v[4:5]
	v_cvt_pk_bf16_f32 v37, v6, v7
	v_cvt_pk_bf16_f32 v36, v4, v5
	v_mov_b32_e32 v38, v33
	v_mov_b32_e32 v39, v29
	global_store_dwordx2 v[100:101], v[36:37], off offset:3584
	v_mov_b32_e32 v36, v32
	v_mov_b32_e32 v37, v28
	v_pk_mul_f32 v[38:39], v[38:39], v[38:39]
	v_mov_b32_e32 v64, v35
	v_mov_b32_e32 v65, v31
	v_pk_fma_f32 v[36:37], v[36:37], v[36:37], v[38:39]
	v_mov_b32_e32 v38, v34
	v_mov_b32_e32 v39, v30
	v_pk_mul_f32 v[64:65], v[64:65], v[64:65]
	s_nop 0
	v_pk_fma_f32 v[38:39], v[38:39], v[38:39], v[64:65]
	v_pk_mul_f32 v[64:65], v[26:27], v[26:27]
	v_pk_add_f32 v[36:37], v[36:37], v[38:39]
	v_pk_mul_f32 v[38:39], v[24:25], v[24:25]
	v_pk_add_f32 v[36:37], v[36:37], v[36:37] op_sel_hi:[0,1]
	v_pk_mov_b32 v[66:67], v[38:39], v[64:65] op_sel:[1,0]
	v_mov_b32_e32 v39, v65
	v_mul_f32_e32 v36, v20, v20
	v_pk_add_f32 v[38:39], v[66:67], v[38:39]
	v_pk_fma_f32 v[64:65], v[20:21], v[20:21], v[36:37] op_sel_hi:[1,1,0]
	v_mul_f32_e32 v36, v22, v22
	v_pk_add_f32 v[38:39], v[38:39], v[38:39] op_sel_hi:[0,1]
	v_pk_fma_f32 v[66:67], v[22:23], v[22:23], v[36:37] op_sel_hi:[1,1,0]
	v_mul_f32_e32 v64, v16, v16
	v_mul_f32_e32 v66, v17, v17
	v_mul_f32_e32 v38, v18, v18
	v_mul_f32_e32 v36, v19, v19
	v_pk_add_f32 v[64:65], v[64:65], v[66:67]
	v_pk_add_f32 v[36:37], v[38:39], v[36:37]
	v_pk_mul_f32 v[38:39], v[12:13], v[12:13]
	v_pk_add_f32 v[36:37], v[64:65], v[36:37]
	v_pk_mul_f32 v[64:65], v[14:15], v[14:15]
	v_pk_add_f32 v[36:37], v[36:37], v[36:37] op_sel_hi:[0,1]
	v_pk_mov_b32 v[66:67], v[38:39], v[64:65] op_sel:[1,0]
	v_mov_b32_e32 v39, v65
	v_mul_f32_e32 v36, v8, v8
	v_pk_add_f32 v[38:39], v[66:67], v[38:39]
	v_pk_fma_f32 v[64:65], v[8:9], v[8:9], v[36:37] op_sel_hi:[1,1,0]
	v_mul_f32_e32 v36, v10, v10
	v_pk_add_f32 v[38:39], v[38:39], v[38:39] op_sel_hi:[0,1]
	v_pk_fma_f32 v[66:67], v[10:11], v[10:11], v[36:37] op_sel_hi:[1,1,0]
	v_mul_f32_e32 v64, v4, v4
	v_mul_f32_e32 v66, v5, v5
	v_mul_f32_e32 v38, v6, v6
	v_mul_f32_e32 v36, v7, v7
	v_pk_add_f32 v[64:65], v[64:65], v[66:67]
	v_pk_add_f32 v[36:37], v[38:39], v[36:37]
	s_nop 0
	v_pk_add_f32 v[36:37], v[64:65], v[36:37]
	v_add_f32_e32 v36, v36, v37
	s_waitcnt lgkmcnt(0)
; __device__ __forceinline__ void row_post1(const Params& p, int layer) {
;     ...
;         const float rs2 = row_rstd(x);
; #pragma unroll
;         for (int j = 0; j < 8; ++j) { const f32x4 g = *(const f32x4*)(g2 + 256 * j + 4 * lane); x[j] = x[j] * rs2 * g; }
;         row_store_bf16((bf16_t*)(ws + WS_HB) + (size_t)m * D, lane, x);
	s_nop 1
	v_add_f32_dpp v36, v36, v36 quad_perm:[1,0,3,2] row_mask:0xf bank_mask:0xf bound_ctrl:1
	s_nop 1
	v_add_f32_dpp v36, v36, v36 quad_perm:[2,3,0,1] row_mask:0xf bank_mask:0xf bound_ctrl:1
	s_nop 1
	v_add_f32_dpp v36, v36, v36 row_half_mirror row_mask:0xf bank_mask:0xf bound_ctrl:1
	s_nop 1
	v_add_f32_dpp v36, v36, v36 row_mirror row_mask:0xf bank_mask:0xf bound_ctrl:1
	s_nop 1
	v_add_f32_dpp v36, v36, v36 row_bcast:15 row_mask:0xa bank_mask:0xf
	s_nop 1
	v_add_f32_dpp v36, v36, v36 row_bcast:31 row_mask:0xc bank_mask:0xf
	s_nop 1
	v_readlane_b32 vcc_lo, v36, 63
	s_nop 2
	v_mov_b32_e32 v36, vcc_lo
	v_fmamk_f32 v36, v36, 0x3a000000, v147
	v_cmp_gt_f32_e32 vcc, s29, v36
	v_mul_f32_e32 v37, 0x4b800000, v36
	s_nop 0
	v_cndmask_b32_e32 v36, v36, v37, vcc
	v_rsq_f32_e32 v36, v36
	s_nop 0
	v_mul_f32_e32 v37, 0x45800000, v36
	v_cndmask_b32_e32 v36, v36, v37, vcc
	v_pk_mul_f32 v[32:33], v[32:33], v[36:37] op_sel_hi:[1,0]
	v_pk_mul_f32 v[34:35], v[34:35], v[36:37] op_sel_hi:[1,0]
	v_pk_mul_f32 v[28:29], v[28:29], v[36:37] op_sel_hi:[1,0]
	v_pk_mul_f32 v[30:31], v[30:31], v[36:37] op_sel_hi:[1,0]
	v_pk_mul_f32 v[24:25], v[24:25], v[36:37] op_sel_hi:[1,0]
	v_pk_mul_f32 v[26:27], v[26:27], v[36:37] op_sel_hi:[1,0]
	v_pk_mul_f32 v[20:21], v[20:21], v[36:37] op_sel_hi:[1,0]
	v_pk_mul_f32 v[22:23], v[22:23], v[36:37] op_sel_hi:[1,0]
	v_pk_mul_f32 v[16:17], v[16:17], v[36:37] op_sel_hi:[1,0]
	v_pk_mul_f32 v[18:19], v[18:19], v[36:37] op_sel_hi:[1,0]
	v_pk_mul_f32 v[12:13], v[12:13], v[36:37] op_sel_hi:[1,0]
	v_pk_mul_f32 v[14:15], v[14:15], v[36:37] op_sel_hi:[1,0]
	v_pk_mul_f32 v[8:9], v[8:9], v[36:37] op_sel_hi:[1,0]
	v_pk_mul_f32 v[10:11], v[10:11], v[36:37] op_sel_hi:[1,0]
	v_pk_mul_f32 v[4:5], v[4:5], v[36:37] op_sel_hi:[1,0]
	v_pk_mul_f32 v[6:7], v[6:7], v[36:37] op_sel_hi:[1,0]
	v_pk_mul_f32 v[38:39], v[194:195], v[34:35]
	v_pk_mul_f32 v[64:65], v[192:193], v[32:33]
	v_pk_mul_f32 v[34:35], v[198:199], v[30:31]
	v_pk_mul_f32 v[32:33], v[196:197], v[28:29]
	v_pk_mul_f32 v[30:31], v[202:203], v[26:27]
	v_pk_mul_f32 v[28:29], v[200:201], v[24:25]
	v_pk_mul_f32 v[26:27], v[206:207], v[22:23]
	v_pk_mul_f32 v[24:25], v[204:205], v[20:21]
	v_pk_mul_f32 v[22:23], v[210:211], v[18:19]
	v_pk_mul_f32 v[20:21], v[208:209], v[16:17]
	v_pk_mul_f32 v[18:19], v[214:215], v[14:15]
	v_pk_mul_f32 v[16:17], v[212:213], v[12:13]
	v_pk_mul_f32 v[14:15], v[218:219], v[10:11]
	v_pk_mul_f32 v[12:13], v[216:217], v[8:9]
	v_pk_mul_f32 v[6:7], v[222:223], v[6:7]
	v_pk_mul_f32 v[4:5], v[220:221], v[4:5]
	v_lshl_add_u64 v[8:9], v[46:47], 0, s[6:7]
	v_cvt_pk_bf16_f32 v10, v64, v65
	v_cvt_pk_bf16_f32 v11, v38, v39
	global_store_dwordx2 v[8:9], v[10:11], off
	v_cvt_pk_bf16_f32 v10, v32, v33
	v_cvt_pk_bf16_f32 v11, v34, v35
	global_store_dwordx2 v[8:9], v[10:11], off offset:512
	v_cvt_pk_bf16_f32 v10, v28, v29
	v_cvt_pk_bf16_f32 v11, v30, v31
	global_store_dwordx2 v[8:9], v[10:11], off offset:1024
	v_cvt_pk_bf16_f32 v10, v24, v25
	v_cvt_pk_bf16_f32 v11, v26, v27
	global_store_dwordx2 v[8:9], v[10:11], off offset:1536
	v_cvt_pk_bf16_f32 v10, v20, v21
	v_cvt_pk_bf16_f32 v11, v22, v23
	global_store_dwordx2 v[8:9], v[10:11], off offset:2048
	v_cvt_pk_bf16_f32 v10, v16, v17
	v_cvt_pk_bf16_f32 v11, v18, v19
	global_store_dwordx2 v[8:9], v[10:11], off offset:2560
	v_cvt_pk_bf16_f32 v10, v12, v13
	v_cvt_pk_bf16_f32 v11, v14, v15
	v_cvt_pk_bf16_f32 v4, v4, v5
	v_cvt_pk_bf16_f32 v5, v6, v7
	s_cselect_b64 s[6:7], -1, 0
	global_store_dwordx2 v[8:9], v[10:11], off offset:3072
	global_store_dwordx2 v[8:9], v[4:5], off offset:3584

; __device__ __forceinline__ unsigned pk2(float lo, float hi) { f32x2c v = {lo, hi}; return __builtin_bit_cast(unsigned, __builtin_convertvector(v, bf16x2c)); }
; __device__ __forceinline__ float sigmoidf_(float x) { return __builtin_amdgcn_rcpf(1.0f + __expf(-x)); }
; __device__ __forceinline__ void row_hg(const Params& p, int e) {
;     ...
;     for (int m = gw; m < M; m += ngw) {
;         f32x4 v[4]; float s = 0.f;
; #pragma unroll
;         for (int j = 0; j < 4; ++j) { v[j] = *(const f32x4*)(O0 + (size_t)m * 1024 + 256 * j + 4 * lane); if (m >= MP) v[j] += *(const f32x4*)(O1 + (size_t)m * 1024 + 256 * j + 4 * lane);
;             s += (v[j][0] * v[j][0] + v[j][1] * v[j][1]) + (v[j][2] * v[j][2] + v[j][3] * v[j][3]); }
;         const float rs = rsqrtf(wave_sum(s) * (1.f / 1024.f) + 1e-6f);
; #pragma unroll
;         for (int j = 0; j < 4; ++j) { const f32x4 gg = *(const f32x4*)(g + 256 * j + 4 * lane); const f32x4 ga = *(const f32x4*)(PROJ + (size_t)m * IN_EVEN + 3072 + 256 * j + 4 * lane);
;             f32x4 y = v[j] * rs * gg;
; #pragma unroll
;             for (int q = 0; q < 4; ++q) y[q] *= ga[q] * sigmoidf_(ga[q]);
;             u32x2 w; w.x = pk2(y[0], y[1]); w.y = pk2(y[2], y[3]); *(u32x2*)(MA + (size_t)m * D + 256 * j + 4 * lane) = w; }
.LBB0_1001:
	s_waitcnt vmcnt(3)
	v_mul_f32_e32 v2, v17, v17
	v_mul_f32_e32 v26, v19, v19
	v_fmac_f32_e32 v2, v16, v16
	v_fmac_f32_e32 v26, v18, v18
	v_add_f32_e32 v2, v2, v26
	s_waitcnt vmcnt(2)
	v_mul_f32_e32 v26, v13, v13
	v_mul_f32_e32 v27, v15, v15
	v_fmac_f32_e32 v26, v12, v12
	v_fmac_f32_e32 v27, v14, v14
	v_add_f32_e32 v26, v26, v27
	v_add_f32_e32 v2, v2, v26
	s_waitcnt vmcnt(1)
	v_mul_f32_e32 v26, v9, v9
	v_mul_f32_e32 v27, v11, v11
	v_fmac_f32_e32 v26, v8, v8
	v_fmac_f32_e32 v27, v10, v10
	v_add_f32_e32 v26, v26, v27
	v_add_f32_e32 v2, v2, v26
	s_waitcnt vmcnt(0)
	v_pk_mul_f32 v[26:27], v[6:7], v[6:7]
	v_pk_mul_f32 v[28:29], v[4:5], v[4:5]
	s_mov_b32 s3, 0x1b203000
	v_pk_mov_b32 v[36:37], v[28:29], v[26:27] op_sel:[1,0]
	v_mov_b32_e32 v29, v27
	v_pk_add_f32 v[26:27], v[36:37], v[28:29]
	v_add_f32_e32 v26, v26, v27
	v_add_f32_e32 v2, v2, v26
	v_lshl_add_u64 v[28:29], s[10:11], 0, v[20:21]
	s_add_i32 s2, s2, s8
	v_lshl_add_u64 v[20:21], v[20:21], 0, s[12:13]
	v_lshl_add_u64 v[24:25], v[24:25], 0, s[12:13]
	s_cmpk_gt_i32 s2, 0x20ff
	s_waitcnt lgkmcnt(0)
	s_nop 1
	v_add_f32_dpp v2, v2, v2 quad_perm:[1,0,3,2] row_mask:0xf bank_mask:0xf bound_ctrl:1
	s_nop 1
	v_add_f32_dpp v2, v2, v2 quad_perm:[2,3,0,1] row_mask:0xf bank_mask:0xf bound_ctrl:1
	s_nop 1
	v_add_f32_dpp v2, v2, v2 row_half_mirror row_mask:0xf bank_mask:0xf bound_ctrl:1
	s_nop 1
	v_add_f32_dpp v2, v2, v2 row_mirror row_mask:0xf bank_mask:0xf bound_ctrl:1
	s_nop 1
	v_add_f32_dpp v2, v2, v2 row_bcast:15 row_mask:0xa bank_mask:0xf
	s_nop 1
	v_add_f32_dpp v2, v2, v2 row_bcast:31 row_mask:0xc bank_mask:0xf
	s_nop 1
	v_readlane_b32 vcc_lo, v2, 63
	s_nop 2
	v_mov_b32_e32 v2, vcc_lo
	v_fmamk_f32 v2, v2, 0x3a800000, v147
	v_cmp_gt_f32_e32 vcc, s29, v2
	v_mul_f32_e32 v26, 0x4b800000, v2
	s_nop 0
	v_cndmask_b32_e32 v2, v2, v26, vcc
	v_rsq_f32_e32 v2, v2
	s_nop 0
	v_mul_f32_e32 v26, 0x45800000, v2
	v_cndmask_b32_e32 v2, v2, v26, vcc
	v_lshl_add_u64 v[26:27], s[10:11], 0, v[22:23]
	v_add_co_u32_e32 v26, vcc, s3, v26
	v_pk_mul_f32 v[16:17], v[16:17], v[2:3] op_sel_hi:[1,0]
	s_nop 0
	v_addc_co_u32_e32 v27, vcc, 0, v27, vcc
	global_load_dwordx4 v[80:83], v[26:27], off
	global_load_dwordx4 v[84:87], v[26:27], off offset:1024
	global_load_dwordx4 v[88:91], v[26:27], off offset:2048
	global_load_dwordx4 v[92:95], v[26:27], off offset:3072
	v_pk_mul_f32 v[18:19], v[18:19], v[2:3] op_sel_hi:[1,0]
	v_pk_mul_f32 v[12:13], v[12:13], v[2:3] op_sel_hi:[1,0]
	v_pk_mul_f32 v[14:15], v[14:15], v[2:3] op_sel_hi:[1,0]
	v_pk_mul_f32 v[8:9], v[8:9], v[2:3] op_sel_hi:[1,0]
	v_pk_mul_f32 v[10:11], v[10:11], v[2:3] op_sel_hi:[1,0]
	v_pk_mul_f32 v[4:5], v[4:5], v[2:3] op_sel_hi:[1,0]
	v_pk_mul_f32 v[6:7], v[6:7], v[2:3] op_sel_hi:[1,0]
	v_lshl_add_u64 v[22:23], v[22:23], 0, s[14:15]
	v_pk_mul_f32 v[16:17], v[60:61], v[16:17]
	v_pk_mul_f32 v[18:19], v[62:63], v[18:19]
	s_waitcnt vmcnt(3)
	v_mul_f32_e32 v36, 0xbfb8aa3b, v80
	v_mul_f32_e32 v37, 0xbfb8aa3b, v81
	v_exp_f32_e32 v36, v36
	v_exp_f32_e32 v37, v37
	v_add_f32_e32 v36, 1.0, v36
	v_add_f32_e32 v37, 1.0, v37
	v_rcp_f32_e32 v36, v36
	v_rcp_f32_e32 v37, v37
	s_nop 0
	v_pk_mul_f32 v[36:37], v[80:81], v[36:37]
	s_nop 0
	v_pk_mul_f32 v[16:17], v[36:37], v[16:17]
	v_mul_f32_e32 v36, 0xbfb8aa3b, v82
	v_mul_f32_e32 v37, 0xbfb8aa3b, v83
	v_exp_f32_e32 v36, v36
	v_exp_f32_e32 v37, v37
	v_add_f32_e32 v36, 1.0, v36
	v_add_f32_e32 v37, 1.0, v37
	v_rcp_f32_e32 v36, v36
	v_rcp_f32_e32 v37, v37
	s_nop 0
	v_pk_mul_f32 v[36:37], v[82:83], v[36:37]
	s_nop 0
	v_pk_mul_f32 v[36:37], v[36:37], v[18:19]
	v_cvt_pk_bf16_f32 v18, v16, v17
	v_add_co_u32_e32 v16, vcc, s61, v28
	v_cvt_pk_bf16_f32 v19, v36, v37
	s_nop 0
	v_addc_co_u32_e32 v17, vcc, 0, v29, vcc
	global_store_dwordx2 v[16:17], v[18:19], off
	v_pk_mul_f32 v[12:13], v[64:65], v[12:13]
	s_waitcnt vmcnt(3)
	v_mul_f32_e32 v18, 0xbfb8aa3b, v84
	v_mul_f32_e32 v19, 0xbfb8aa3b, v85
	v_exp_f32_e32 v18, v18
	v_exp_f32_e32 v19, v19
	v_pk_mul_f32 v[14:15], v[66:67], v[14:15]
	v_add_f32_e32 v18, 1.0, v18
	v_add_f32_e32 v19, 1.0, v19
	v_rcp_f32_e32 v18, v18
	v_rcp_f32_e32 v19, v19
	s_nop 0
	v_pk_mul_f32 v[18:19], v[84:85], v[18:19]
	s_nop 0
	v_pk_mul_f32 v[12:13], v[18:19], v[12:13]
	v_mul_f32_e32 v18, 0xbfb8aa3b, v86
	v_mul_f32_e32 v19, 0xbfb8aa3b, v87
	v_exp_f32_e32 v18, v18
	v_exp_f32_e32 v19, v19
	v_cvt_pk_bf16_f32 v12, v12, v13
	v_add_f32_e32 v18, 1.0, v18
	v_add_f32_e32 v19, 1.0, v19
	v_rcp_f32_e32 v18, v18
	v_rcp_f32_e32 v19, v19
	s_nop 0
	v_pk_mul_f32 v[18:19], v[86:87], v[18:19]
	s_nop 0
	v_pk_mul_f32 v[14:15], v[18:19], v[14:15]
	s_nop 0
	v_cvt_pk_bf16_f32 v13, v14, v15
	global_store_dwordx2 v[16:17], v[12:13], off offset:512
	s_nop 0
	v_pk_mul_f32 v[8:9], v[68:69], v[8:9]
	s_waitcnt vmcnt(3)
	v_mul_f32_e32 v12, 0xbfb8aa3b, v88
	v_mul_f32_e32 v13, 0xbfb8aa3b, v89
	v_exp_f32_e32 v12, v12
	v_exp_f32_e32 v13, v13
	v_pk_mul_f32 v[10:11], v[70:71], v[10:11]
	v_add_f32_e32 v12, 1.0, v12
	v_add_f32_e32 v13, 1.0, v13
	v_rcp_f32_e32 v12, v12
	v_rcp_f32_e32 v13, v13
	s_nop 0
	v_pk_mul_f32 v[12:13], v[88:89], v[12:13]
	s_nop 0
	v_pk_mul_f32 v[8:9], v[12:13], v[8:9]
	v_mul_f32_e32 v12, 0xbfb8aa3b, v90
	v_mul_f32_e32 v13, 0xbfb8aa3b, v91
	v_exp_f32_e32 v12, v12
	v_exp_f32_e32 v13, v13
	v_cvt_pk_bf16_f32 v8, v8, v9
	v_add_f32_e32 v12, 1.0, v12
	v_add_f32_e32 v13, 1.0, v13
	v_rcp_f32_e32 v12, v12
	v_rcp_f32_e32 v13, v13
	s_nop 0
	v_pk_mul_f32 v[12:13], v[90:91], v[12:13]
	s_nop 0
	v_pk_mul_f32 v[10:11], v[12:13], v[10:11]
	s_nop 0
	v_cvt_pk_bf16_f32 v9, v10, v11
	global_store_dwordx2 v[16:17], v[8:9], off offset:1024
	s_nop 0
	v_pk_mul_f32 v[4:5], v[72:73], v[4:5]
	s_waitcnt vmcnt(3)
	v_mul_f32_e32 v2, 0xbfb8aa3b, v92
	v_exp_f32_e32 v2, v2
	v_pk_mul_f32 v[6:7], v[74:75], v[6:7]
	v_add_f32_e32 v2, 1.0, v2
	v_rcp_f32_e32 v8, v2
	v_mul_f32_e32 v2, 0xbfb8aa3b, v93
	v_exp_f32_e32 v2, v2
	s_nop 0
	v_add_f32_e32 v2, 1.0, v2
	v_rcp_f32_e32 v9, v2
	v_mul_f32_e32 v2, 0xbfb8aa3b, v94
	v_exp_f32_e32 v2, v2
	v_pk_mul_f32 v[8:9], v[92:93], v[8:9]
	s_nop 0
	v_pk_mul_f32 v[4:5], v[4:5], v[8:9]
	v_add_f32_e32 v2, 1.0, v2
	v_rcp_f32_e32 v8, v2
	v_mul_f32_e32 v2, 0xbfb8aa3b, v95
	v_exp_f32_e32 v2, v2
	v_cvt_pk_bf16_f32 v4, v4, v5
	v_add_f32_e32 v2, 1.0, v2
	v_rcp_f32_e32 v9, v2
	s_nop 0
	v_pk_mul_f32 v[8:9], v[94:95], v[8:9]
	s_nop 0
	v_pk_mul_f32 v[6:7], v[6:7], v[8:9]
	s_nop 0
	v_cvt_pk_bf16_f32 v5, v6, v7
	global_store_dwordx2 v[16:17], v[4:5], off offset:1536
	s_cbranch_scc1 .LBB0_1010
